# loop-edge edit: attention KV loop back edge folded to one conditional branch (s_mov s3,s2 + s_cbranch_scc1 top, fall-through exit)
# speedup vs baseline: 1.0036x; 1.0036x over previous
.LBB0_381:
	s_barrier
	s_mulk_i32 s3, 0x2400
	v_add3_u32 v190, v143, s3, v142
	v_add_u32_e32 v191, 0x6800, v190
	v_add_u32_e32 v192, 0x7a00, v190
	ds_read2_b64 v[194:197], v191 offset1:2
	ds_read2_b64 v[198:201], v192 offset1:2
	ds_read2_b64 v[202:205], v191 offset0:4 offset1:6
	ds_read2_b64 v[206:209], v192 offset0:4 offset1:6
	ds_read2_b64 v[210:213], v191 offset0:8 offset1:10
	ds_read2_b64 v[214:217], v192 offset0:8 offset1:10
	ds_read2_b64 v[218:221], v191 offset0:12 offset1:14
	ds_read2_b64 v[222:225], v192 offset0:12 offset1:14
	v_exp_f32_e32 v32, v32
	v_exp_f32_e32 v33, v33
	v_exp_f32_e32 v34, v34
	v_exp_f32_e32 v35, v35
	v_exp_f32_e32 v36, v36
	v_exp_f32_e32 v37, v37
	v_exp_f32_e32 v38, v38
	v_exp_f32_e32 v39, v39
	v_cvt_pk_bf16_f32 v160, v32, v33
	v_cvt_pk_bf16_f32 v161, v34, v35
	v_cvt_pk_bf16_f32 v162, v36, v37
	v_cvt_pk_bf16_f32 v163, v38, v39
	v_add_f32_e32 v168, v32, v33
	v_add_f32_e32 v169, v34, v35
	v_add_f32_e32 v168, v168, v36
	v_add_f32_e32 v169, v169, v37
	v_add_f32_e32 v168, v168, v38
	v_add_f32_e32 v169, v169, v39
	s_waitcnt lgkmcnt(6)
	v_mfma_f32_32x32x16_bf16 v[16:31], v[194:197], v[160:163], v[16:31]
	v_mfma_f32_32x32x16_bf16 v[0:15], v[198:201], v[160:163], v[0:15]
	v_exp_f32_e32 v40, v40
	v_exp_f32_e32 v41, v41
	v_exp_f32_e32 v42, v42
	v_exp_f32_e32 v43, v43
	v_exp_f32_e32 v44, v44
	v_exp_f32_e32 v45, v45
	v_exp_f32_e32 v46, v46
	v_exp_f32_e32 v47, v47
	v_cvt_pk_bf16_f32 v164, v40, v41
	v_cvt_pk_bf16_f32 v165, v42, v43
	v_cvt_pk_bf16_f32 v166, v44, v45
	v_cvt_pk_bf16_f32 v167, v46, v47
	v_add_f32_e32 v168, v168, v40
	v_add_f32_e32 v169, v169, v41
	v_add_f32_e32 v168, v168, v42
	v_add_f32_e32 v169, v169, v43
	v_add_f32_e32 v168, v168, v44
	v_add_f32_e32 v169, v169, v45
	v_add_f32_e32 v168, v168, v46
	v_add_f32_e32 v169, v169, v47
	s_waitcnt lgkmcnt(4)
	v_mfma_f32_32x32x16_bf16 v[16:31], v[202:205], v[164:167], v[16:31]
	v_mfma_f32_32x32x16_bf16 v[0:15], v[206:209], v[164:167], v[0:15]
	v_exp_f32_e32 v48, v48
	v_exp_f32_e32 v49, v49
	v_exp_f32_e32 v50, v50
	v_exp_f32_e32 v51, v51
	v_exp_f32_e32 v52, v52
	v_exp_f32_e32 v53, v53
	v_exp_f32_e32 v54, v54
	v_exp_f32_e32 v55, v55
	v_cvt_pk_bf16_f32 v160, v48, v49
	v_cvt_pk_bf16_f32 v161, v50, v51
	v_cvt_pk_bf16_f32 v162, v52, v53
	v_cvt_pk_bf16_f32 v163, v54, v55
	v_add_f32_e32 v168, v168, v48
	v_add_f32_e32 v169, v169, v49
	v_add_f32_e32 v168, v168, v50
	v_add_f32_e32 v169, v169, v51
	v_add_f32_e32 v168, v168, v52
	v_add_f32_e32 v169, v169, v53
	v_add_f32_e32 v168, v168, v54
	v_add_f32_e32 v169, v169, v55
	s_waitcnt lgkmcnt(2)
	v_mfma_f32_32x32x16_bf16 v[16:31], v[210:213], v[160:163], v[16:31]
	v_mfma_f32_32x32x16_bf16 v[0:15], v[214:217], v[160:163], v[0:15]
	v_exp_f32_e32 v56, v56
	v_exp_f32_e32 v57, v57
	v_exp_f32_e32 v58, v58
	v_exp_f32_e32 v59, v59
	v_exp_f32_e32 v60, v60
	v_exp_f32_e32 v61, v61
	v_exp_f32_e32 v62, v62
	v_exp_f32_e32 v63, v63
	v_cvt_pk_bf16_f32 v164, v56, v57
	v_cvt_pk_bf16_f32 v165, v58, v59
	v_cvt_pk_bf16_f32 v166, v60, v61
	v_cvt_pk_bf16_f32 v167, v62, v63
	v_add_f32_e32 v168, v168, v56
	v_add_f32_e32 v169, v169, v57
	v_add_f32_e32 v168, v168, v58
	v_add_f32_e32 v169, v169, v59
	v_add_f32_e32 v168, v168, v60
	v_add_f32_e32 v169, v169, v61
	v_add_f32_e32 v168, v168, v62
	v_add_f32_e32 v169, v169, v63
	v_add_f32_e32 v168, v168, v169
	v_add_f32_e32 v119, v119, v168
	s_add_i32 s1, s1, 64
	s_cmpk_lg_i32 s1, 0x11c0
	s_waitcnt lgkmcnt(0)
	s_barrier
	v_mfma_f32_32x32x16_bf16 v[16:31], v[218:221], v[164:167], v[16:31]
	v_mfma_f32_32x32x16_bf16 v[0:15], v[222:225], v[164:167], v[0:15]
	s_mov_b32 s3, s2
	s_cbranch_scc1 .LBB0_377
